# v17
# speedup vs baseline: 1.0033x; 1.0014x over previous
.LBB0_66:
	s_waitcnt lgkmcnt(2)
	s_barrier
	v_add_u32_e32 v189, s100, v153
	s_waitcnt lgkmcnt(1)
	v_mfma_f32_32x32x16_bf16 v[80:95], v[228:231], v[108:111], v[196:211]
	ds_read_b128 v[228:231], v194 offset:8192
	s_waitcnt lgkmcnt(1)
	v_mfma_f32_32x32x16_bf16 v[64:79], v[224:227], v[108:111], v[196:211]
	ds_read_b128 v[224:227], v194 offset:12288
	s_waitcnt lgkmcnt(1)
	v_mfma_f32_32x32x16_bf16 v[80:95], v[228:231], v[104:107], v[80:95]
	ds_read_b128 v[228:231], v232 offset:8192
	s_waitcnt lgkmcnt(1)
	v_mfma_f32_32x32x16_bf16 v[64:79], v[224:227], v[104:107], v[64:79]
	ds_read_b128 v[224:227], v232 offset:12288
	s_waitcnt lgkmcnt(1)
	v_mfma_f32_32x32x16_bf16 v[80:95], v[228:231], v[100:103], v[80:95]
	ds_read_b128 v[228:231], v233 offset:8192
	s_waitcnt lgkmcnt(1)
	v_mfma_f32_32x32x16_bf16 v[64:79], v[224:227], v[100:103], v[64:79]
	ds_read_b128 v[224:227], v233 offset:12288
	ds_read_b64_tr_b16 v[212:213], v189 offset:0
	ds_read_b64_tr_b16 v[214:215], v189 offset:0x800
	ds_read_b64_tr_b16 v[216:217], v189 offset:0x1000
	ds_read_b64_tr_b16 v[218:219], v189 offset:0x1800
	ds_read_b64_tr_b16 v[220:221], v189 offset:0x2000
	ds_read_b64_tr_b16 v[222:223], v189 offset:0x2800
	s_waitcnt lgkmcnt(7)
	v_mfma_f32_32x32x16_bf16 v[80:95], v[228:231], v[96:99], v[80:95]
	s_waitcnt lgkmcnt(6)
	v_mfma_f32_32x32x16_bf16 v[64:79], v[224:227], v[96:99], v[64:79]
	ds_read_b64_tr_b16 v[224:225], v189 offset:0x3000
	ds_read_b64_tr_b16 v[226:227], v189 offset:0x3800
	s_cmp_eq_u32 s67, s22
	s_cbranch_scc1 .LBB0_61
	s_add_u32 s10, s22, 0xc0000
	s_cmp_eq_u32 s67, s10
	s_cbranch_scc1 .Lda1_sl_last
	s_add_u32 s10, s77, s22
	s_addc_u32 s11, s66, s23
	s_add_u32 s48, s10, 0x12783400
	s_addc_u32 s49, s11, 0
	s_add_u32 s50, s77, s22
	s_addc_u32 s51, s66, s23
	s_add_u32 s50, s50, 0x12782c00
	s_addc_u32 s51, s51, 0
	global_load_dwordx4 v[128:131], v156, s[48:49]
	global_load_dwordx4 v[124:127], v158, s[48:49]
	global_load_dwordx4 v[132:135], v160, s[50:51]
	global_load_dwordx4 v[112:115], v166, s[48:49]
	global_load_dwordx4 v[116:119], v164, s[48:49]
	global_load_dwordx4 v[120:123], v162, s[50:51]
	s_branch .LBB0_61

.LBB0_102:
	s_waitcnt lgkmcnt(2)
	s_barrier
	v_add_u32_e32 v189, s100, v153
	s_waitcnt lgkmcnt(1)
	v_mfma_f32_32x32x16_bf16 v[80:95], v[228:231], v[108:111], v[196:211]
	ds_read_b128 v[228:231], v194 offset:8192
	s_waitcnt lgkmcnt(1)
	v_mfma_f32_32x32x16_bf16 v[64:79], v[224:227], v[108:111], v[196:211]
	ds_read_b128 v[224:227], v194 offset:12288
	s_waitcnt lgkmcnt(1)
	v_mfma_f32_32x32x16_bf16 v[80:95], v[228:231], v[104:107], v[80:95]
	ds_read_b128 v[228:231], v232 offset:8192
	s_waitcnt lgkmcnt(1)
	v_mfma_f32_32x32x16_bf16 v[64:79], v[224:227], v[104:107], v[64:79]
	ds_read_b128 v[224:227], v232 offset:12288
	s_waitcnt lgkmcnt(1)
	v_mfma_f32_32x32x16_bf16 v[80:95], v[228:231], v[100:103], v[80:95]
	ds_read_b128 v[228:231], v233 offset:8192
	s_waitcnt lgkmcnt(1)
	v_mfma_f32_32x32x16_bf16 v[64:79], v[224:227], v[100:103], v[64:79]
	ds_read_b128 v[224:227], v233 offset:12288
	ds_read_b64_tr_b16 v[212:213], v189 offset:0
	ds_read_b64_tr_b16 v[214:215], v189 offset:0x800
	ds_read_b64_tr_b16 v[216:217], v189 offset:0x1000
	ds_read_b64_tr_b16 v[218:219], v189 offset:0x1800
	ds_read_b64_tr_b16 v[220:221], v189 offset:0x2000
	ds_read_b64_tr_b16 v[222:223], v189 offset:0x2800
	s_waitcnt lgkmcnt(7)
	v_mfma_f32_32x32x16_bf16 v[80:95], v[228:231], v[96:99], v[80:95]
	s_waitcnt lgkmcnt(6)
	v_mfma_f32_32x32x16_bf16 v[64:79], v[224:227], v[96:99], v[64:79]
	ds_read_b64_tr_b16 v[224:225], v189 offset:0x3000
	ds_read_b64_tr_b16 v[226:227], v189 offset:0x3800
	s_cmp_eq_u32 s67, s40
	s_cbranch_scc1 .LBB0_97
	s_add_u32 s10, s40, 0xc0000
	s_cmp_eq_u32 s67, s10
	s_cbranch_scc1 .Lda2_sl_last
	s_add_u32 s10, s77, s40
	s_addc_u32 s11, s66, s41
	s_add_u32 s42, s10, 0x12783400
	s_addc_u32 s43, s11, 0
	s_add_u32 s25, s77, s40
	s_addc_u32 s45, s66, s41
	s_add_u32 s44, s25, 0x12782c80
	s_addc_u32 s45, s45, 0
	global_load_dwordx4 v[128:131], v156, s[42:43]
	global_load_dwordx4 v[124:127], v158, s[42:43]
	global_load_dwordx4 v[132:135], v160, s[44:45]
	global_load_dwordx4 v[112:115], v166, s[42:43]
	global_load_dwordx4 v[116:119], v164, s[42:43]
	global_load_dwordx4 v[120:123], v162, s[44:45]
	s_branch .LBB0_97
